# v60 + s4 task queue made static (pass-C block = wgid, latent unit = 256+wgid, ctx units on 32 fixed light WGs): no dequeue atomics
# baseline (speedup 1.0000x reference)
.LBB0_336:
	s_and_b64 vcc, exec, s[0:1]
	s_cbranch_vccz .LBB0_376
	v_readlane_b32 s0, v255, 16
	v_readlane_b32 s1, v255, 17
	s_and_b64 s[0:1], s[0:1], exec
	s_movk_i32 s0, 0x220
	s_cselect_b32 s8, s0, 0x200
	s_sub_i32 s0, s94, 32
	s_cmp_lt_u32 s0, 10
	v_readlane_b32 s0, v254, 28
	s_cselect_b64 s[18:19], -1, 0
	v_readlane_b32 s1, v254, 29
	s_add_u32 s28, s0, 0x19300000
	s_addc_u32 s29, s1, 0
	v_readlane_b32 s2, v255, 7
	s_add_u32 s36, s0, 0x16f00000
	v_readlane_b32 s3, v255, 8
	s_addc_u32 s37, s1, 0
	s_lshl_b64 s[2:3], s[2:3], 2
	s_add_u32 s42, s0, s2
	v_writelane_b32 v255, s2, 18
	s_addc_u32 s43, s1, s3
	s_add_u32 s9, s0, 0xb200600
	s_addc_u32 s10, s1, 0
	v_writelane_b32 v255, s3, 19
	s_add_u32 s2, s0, 0x2800
	s_addc_u32 s3, s1, 0
	v_writelane_b32 v255, s2, 20
	s_nop 1
	v_writelane_b32 v255, s3, 21
	s_add_u32 s2, s0, 0xa000000
	s_addc_u32 s3, s1, 0
	v_writelane_b32 v255, s2, 22
	s_nop 1
	v_writelane_b32 v255, s3, 23
	s_add_u32 s2, s0, 0x19301100
	s_addc_u32 s3, s1, 0
	v_writelane_b32 v255, s2, 24
	s_add_u32 s46, s0, 0x19300100
	s_addc_u32 s47, s1, 0
	v_writelane_b32 v255, s3, 25
	v_writelane_b32 v255, s18, 26
	s_nop 1
	v_writelane_b32 v255, s19, 27
	v_writelane_b32 v255, s28, 28
	s_nop 1
	v_writelane_b32 v255, s29, 29
	v_writelane_b32 v255, s36, 30
	s_nop 1
	v_writelane_b32 v255, s37, 31
	v_writelane_b32 v255, s42, 32
	s_nop 1
	v_writelane_b32 v255, s43, 33
	v_writelane_b32 v255, s9, 34
	v_writelane_b32 v255, s10, 36
	v_writelane_b32 v255, s46, 38
	s_nop 1
	v_writelane_b32 v255, s47, 39
	v_readlane_b32 s100, v252, 8
	s_branch .LBB0_341

.LBB0_341:
	v_mov_b32_e32 v205, v236
	s_nop 0
	v_cmp_eq_u32_e32 vcc, 0, v205
	s_and_saveexec_b64 s[2:3], vcc
	s_cbranch_execz .LBB0_345
	s_mov_b64 s[6:7], exec
	v_mbcnt_lo_u32_b32 v0, s6, 0
	v_mbcnt_hi_u32_b32 v0, s7, v0
	v_cmp_eq_u32_e32 vcc, 0, v0
	s_and_saveexec_b64 s[4:5], vcc
	s_cbranch_execz .LBB0_344
	s_bcnt1_i32_b64 s6, s[6:7]
	v_mov_b32_e32 v1, s6
	v_mov_b32_e32 v1, s100

.LBB0_345:
	s_or_b64 exec, exec, s[2:3]
	s_waitcnt vmcnt(0) lgkmcnt(0)
	s_barrier
	ds_read_b32 v0, v161 offset:8
	s_mov_b64 s[2:3], -1
	s_waitcnt lgkmcnt(0)
	s_barrier
	v_cmp_le_i32_e32 vcc, s8, v0
	v_readfirstlane_b32 s4, v0
	v_readlane_b32 s101, v252, 8
	s_lshr_b32 s100, s101, 5
	s_lshl_b32 s100, s100, 2
	s_bfe_u32 s101, s101, 0x20001
	s_or_b32 s100, s100, s101
	s_addk_i32 s100, 0x200
	v_readlane_b32 s101, v252, 8
	s_and_b32 s101, s101, 0x19
	s_cmp_eq_u32 s101, 0
	s_cselect_b32 s100, s100, 0x7fffffff
	s_cmpk_lt_u32 s4, 0x200
	s_cselect_b32 s100, s100, 0x7fffffff
	v_readlane_b32 s101, v252, 8
	s_addk_i32 s101, 0x100
	s_cmpk_lt_u32 s4, 0x100
	s_cselect_b32 s100, s101, s100
	s_cbranch_vccnz .LBB0_340
	s_cmpk_gt_i32 s4, 0xff
	s_cbranch_scc0 .LBB0_372
	s_cmpk_gt_u32 s4, 0x1ff
	s_cbranch_scc0 .LBB0_359
	s_add_i32 s2, s4, 0xfffffe00
	s_lshr_b32 s6, s2, 2
	s_lshl_b32 s11, s6, 8
	v_mov_b32_e32 v10, v236
	s_add_i32 s2, s11, 0x4000
	v_readlane_b32 s0, v255, 11
	v_and_b32_e32 v64, 31, v10
	v_ashrrev_i32_e32 v0, 1, v10
	v_and_b32_e32 v0, 0xffffffe0, v0
	v_or_b32_e32 v1, s2, v64
	v_readlane_b32 s1, v255, 12
	v_add_u32_e32 v206, v1, v0
	s_movk_i32 s12, 0x1200
	v_mov_b64_e32 v[0:1], s[0:1]
	v_mad_i64_i32 v[0:1], s[2:3], v206, s12, v[0:1]
	s_and_b32 s7, s4, 3
	s_lshl_b32 s3, s4, 5
	s_lshl_b32 s5, s7, 7
	s_lshl_b32 s64, s7, 8
	v_ashrrev_i32_e32 v50, 3, v10
	s_lshl_b32 s2, s6, 7
	s_and_b32 s7, s3, 64
	v_lshl_add_u64 v[8:9], v[0:1], 0, s[64:65]
	s_or_b32 s64, s7, s2
	v_ashrrev_i32_e32 v51, 31, v50
	v_lshl_add_u64 v[48:49], v[50:51], 0, s[64:65]
	v_mov_b64_e32 v[0:1], s[28:29]
	v_mad_u64_u32 v[0:1], s[2:3], v48, s12, v[0:1]
	s_lshl_b32 s2, s7, 1
	s_add_u32 s2, s9, s2
	s_addc_u32 s3, s10, 0
	s_lshl_b32 s6, s6, 11
	s_or_b32 s7, s11, 0x3800
	v_lshlrev_b32_e32 v2, 4, v10
	v_mov_b32_e32 v56, s7
	v_mov_b32_e32 v57, s6
	v_cmp_gt_i32_e32 vcc, 0, v50
	v_and_b32_e32 v208, 0x70, v2
	v_mov_b32_e32 v209, v161
	v_cndmask_b32_e32 v2, v56, v57, vcc
	s_movk_i32 s16, 0x800
	v_lshl_add_u64 v[210:211], s[2:3], 0, v[208:209]
	v_add3_u32 v2, v50, v2, s16
	v_mad_i32_i24 v1, v49, s12, v1
	v_mad_i64_i32 v[2:3], s[2:3], v2, s12, v[210:211]
	v_lshl_add_u64 v[0:1], v[0:1], 0, v[208:209]
	s_movk_i32 s2, 0x1000
	v_add_co_u32_e32 v54, vcc, s2, v0
	v_bfe_u32 v52, v10, 5, 1
	s_nop 0
	v_addc_co_u32_e32 v55, vcc, 0, v1, vcc
	global_load_dwordx4 v[0:3], v[2:3], off
	s_nop 0
	global_load_dwordx4 v[4:7], v[54:55], off
	v_lshlrev_b32_e32 v212, 4, v52
	v_mov_b32_e32 v213, v161
	v_lshl_add_u64 v[8:9], v[8:9], 0, v[212:213]
	global_load_dwordx4 v[162:165], v[8:9], off offset:512
	global_load_dwordx4 v[166:169], v[8:9], off offset:640
	global_load_dwordx4 v[170:173], v[8:9], off offset:544
	global_load_dwordx4 v[174:177], v[8:9], off offset:672
	global_load_dwordx4 v[178:181], v[8:9], off offset:576
	global_load_dwordx4 v[182:185], v[8:9], off offset:608
	global_load_dwordx4 v[186:189], v[8:9], off offset:704
	global_load_dwordx4 v[190:193], v[8:9], off offset:736
	s_movk_i32 s2, 0x90
	v_mul_lo_u32 v202, v50, s2
	v_and_b32_e32 v120, -8, v10
	v_mad_u32_u24 v65, v64, s2, 16
	v_add3_u32 v10, 16, v202, v208
	v_add_u32_e32 v53, v65, v212
	v_sub_u32_e32 v11, v10, v120
	v_add_u32_e32 v11, 0x2400, v11
	s_movk_i32 s2, 0x88
	v_lshlrev_b32_e32 v214, 3, v52
	v_mul_lo_u32 v203, v50, s2
	v_mul_u32_u24_e32 v209, 0x90, v64
	v_mul_u32_u24_e32 v213, 0x88, v64
	v_readlane_b32 s0, v255, 24
	v_readlane_b32 s1, v255, 25
	s_mov_b32 s11, 1
	v_ashrrev_i32_e32 v207, 31, v206
	s_mov_b32 s17, 0x41000000
	s_waitcnt vmcnt(9)
	ds_write_b128 v10, v[0:3]
	s_waitcnt vmcnt(8)
	ds_write2_b64 v11, v[4:5], v[6:7] offset1:1
	s_waitcnt lgkmcnt(0)
	s_barrier
	ds_read_b128 v[0:3], v53
	ds_read_b128 v[4:7], v53 offset:32
	ds_read_b128 v[8:11], v53 offset:4608
	ds_read_b128 v[12:15], v53 offset:4640
	s_waitcnt vmcnt(7) lgkmcnt(3)
	v_mfma_f32_32x32x16_bf16 v[16:31], v[0:3], v[162:165], 0
	s_waitcnt lgkmcnt(1)
	v_mfma_f32_32x32x16_bf16 v[32:47], v[8:11], v[162:165], 0
	s_waitcnt vmcnt(6)
	v_mfma_f32_32x32x16_bf16 v[88:103], v[0:3], v[166:169], 0
	v_mfma_f32_32x32x16_bf16 v[72:87], v[8:11], v[166:169], 0
	s_waitcnt vmcnt(5)
	v_mfma_f32_32x32x16_bf16 v[16:31], v[4:7], v[170:173], v[16:31]
	s_waitcnt lgkmcnt(0)
	v_mfma_f32_32x32x16_bf16 v[32:47], v[12:15], v[170:173], v[32:47]
	s_waitcnt vmcnt(4)
	v_mfma_f32_32x32x16_bf16 v[88:103], v[4:7], v[174:177], v[88:103]
	ds_read_b128 v[0:3], v53 offset:64
	ds_read_b128 v[4:7], v53 offset:96
	v_mfma_f32_32x32x16_bf16 v[72:87], v[12:15], v[174:177], v[72:87]
	ds_read_b128 v[8:11], v53 offset:4672
	ds_read_b128 v[12:15], v53 offset:4704
	v_mad_u64_u32 v[52:53], s[2:3], v48, s12, 0
	s_movk_i32 s2, 0xffc0
	s_nop 0
	v_cmp_gt_i32_e32 vcc, s2, v50
	s_movk_i32 s2, 0x840
	v_mad_i32_i24 v53, v49, s12, v53
	s_waitcnt vmcnt(3) lgkmcnt(3)
	v_mfma_f32_32x32x16_bf16 v[16:31], v[0:3], v[178:181], v[16:31]
	v_or_b32_e32 v52, v52, v208
	v_lshl_add_u64 v[218:219], s[0:1], 0, v[52:53]
	s_waitcnt lgkmcnt(1)
	v_mfma_f32_32x32x16_bf16 v[32:47], v[8:11], v[178:181], v[32:47]
	s_waitcnt vmcnt(2)
	v_mfma_f32_32x32x16_bf16 v[16:31], v[4:7], v[182:185], v[16:31]
	s_waitcnt vmcnt(1)
	v_mfma_f32_32x32x16_bf16 v[88:103], v[0:3], v[186:189], v[88:103]
	s_nop 9
	v_max_f32_e32 v2, v17, v17
	v_max_f32_e32 v3, v16, v16
	v_max_f32_e32 v2, v3, v2
	v_cndmask_b32_e32 v0, v56, v57, vcc
	v_add3_u32 v0, v50, v0, s2
	v_mad_i64_i32 v[0:1], s[2:3], v0, s12, v[210:211]
	s_waitcnt lgkmcnt(0)
	v_mfma_f32_32x32x16_bf16 v[32:47], v[12:15], v[182:185], v[32:47]
	global_load_dwordx4 v[194:197], v[0:1], off
	global_load_dwordx4 v[198:201], v[54:55], off offset:128
	s_mov_b64 s[2:3], 0x880
	v_lshl_add_u64 v[220:221], v[50:51], 0, s[2:3]
	s_waitcnt vmcnt(2)
	v_mfma_f32_32x32x16_bf16 v[88:103], v[4:7], v[190:193], v[88:103]
	s_nop 5
	v_max3_f32 v4, v18, v19, v33
	v_max3_f32 v2, v2, v32, v34
	v_max3_f32 v3, v4, v22, v23
	v_max3_f32 v2, v2, v35, v20
	v_max3_f32 v3, v3, v38, v39
	v_max3_f32 v2, v2, v21, v36
	v_max3_f32 v3, v3, v26, v27
	v_max3_f32 v2, v2, v37, v24
	v_max3_f32 v3, v3, v42, v43
	v_max3_f32 v2, v2, v25, v40
	v_max3_f32 v3, v3, v30, v31
	v_max3_f32 v2, v2, v41, v28
	v_max3_f32 v3, v3, v46, v47
	v_max3_f32 v2, v2, v29, v44
	v_max3_f32 v2, v2, v45, v3
	v_mov_b32_e32 v3, v2
	s_nop 1
	v_permlane32_swap_b32_e32 v2, v3
	v_max_f32_e32 v3, v3, v3
	v_max_f32_e32 v2, v2, v2
	v_max_f32_e32 v48, v2, v3
	v_sub_f32_e32 v16, v16, v48
	v_sub_f32_e32 v17, v17, v48
	v_sub_f32_e32 v49, v32, v48
	v_sub_f32_e32 v54, v33, v48
	v_exp_f32_e32 v32, v16
	v_exp_f32_e32 v33, v17
	v_sub_f32_e32 v18, v18, v48
	v_sub_f32_e32 v19, v19, v48
	v_exp_f32_e32 v60, v49
	v_exp_f32_e32 v61, v54
	v_sub_f32_e32 v55, v34, v48
	v_sub_f32_e32 v56, v35, v48
	v_exp_f32_e32 v34, v18
	v_exp_f32_e32 v35, v19
	v_sub_f32_e32 v20, v20, v48
	v_sub_f32_e32 v21, v21, v48
	v_exp_f32_e32 v106, v55
	v_exp_f32_e32 v107, v56
	v_sub_f32_e32 v57, v36, v48
	v_sub_f32_e32 v58, v37, v48
	v_pk_add_f32 v[16:17], v[32:33], 0 op_sel_hi:[1,0]
	v_exp_f32_e32 v36, v20
	v_exp_f32_e32 v37, v21
	v_sub_f32_e32 v22, v22, v48
	v_sub_f32_e32 v23, v23, v48
	v_pk_add_f32 v[16:17], v[60:61], v[16:17]
	v_exp_f32_e32 v108, v57
	v_exp_f32_e32 v109, v58
	v_sub_f32_e32 v59, v38, v48
	v_sub_f32_e32 v62, v39, v48
	v_pk_add_f32 v[16:17], v[34:35], v[16:17]
	v_exp_f32_e32 v38, v22
	v_exp_f32_e32 v39, v23
	v_mfma_f32_32x32x16_bf16 v[72:87], v[8:11], v[186:189], v[72:87]
	v_sub_f32_e32 v24, v24, v48
	v_sub_f32_e32 v25, v25, v48
	v_add_f32_e64 v16, v106, v16
	v_add_f32_e64 v17, v107, v17
	v_exp_f32_e32 v110, v59
	v_exp_f32_e32 v111, v62
	v_sub_f32_e32 v40, v40, v48
	v_sub_f32_e32 v41, v41, v48
	v_pk_add_f32 v[16:17], v[36:37], v[16:17]
	v_exp_f32_e32 v112, v24
	v_exp_f32_e32 v113, v25
	v_sub_f32_e32 v26, v26, v48
	v_sub_f32_e32 v27, v27, v48
	v_pk_add_f32 v[16:17], v[108:109], v[16:17]
	v_exp_f32_e32 v54, v40
	v_exp_f32_e32 v55, v41
	v_sub_f32_e32 v42, v42, v48
	v_sub_f32_e32 v43, v43, v48
	v_pk_add_f32 v[16:17], v[38:39], v[16:17]
	v_exp_f32_e32 v114, v26
	v_exp_f32_e32 v115, v27
	v_sub_f32_e32 v28, v28, v48
	v_sub_f32_e32 v29, v29, v48
	v_pk_add_f32 v[16:17], v[110:111], v[16:17]
	v_exp_f32_e32 v56, v42
	v_exp_f32_e32 v57, v43
	v_sub_f32_e32 v44, v44, v48
	v_sub_f32_e32 v45, v45, v48
	v_pk_add_f32 v[16:17], v[112:113], v[16:17]
	v_exp_f32_e32 v116, v28
	v_exp_f32_e32 v117, v29
	v_sub_f32_e32 v30, v30, v48
	v_sub_f32_e32 v31, v31, v48
	v_pk_add_f32 v[16:17], v[54:55], v[16:17]
	v_exp_f32_e32 v58, v44
	v_exp_f32_e32 v59, v45
	v_sub_f32_e32 v46, v46, v48
	v_sub_f32_e32 v47, v47, v48
	v_pk_add_f32 v[16:17], v[114:115], v[16:17]
	v_exp_f32_e32 v118, v30
	v_exp_f32_e32 v119, v31
	v_mfma_f32_32x32x16_bf16 v[72:87], v[12:15], v[190:193], v[72:87]
	v_add_f32_e64 v16, v56, v16
	v_add_f32_e64 v17, v57, v17
	v_exp_f32_e32 v62, v46
	v_exp_f32_e32 v63, v47
	v_pk_add_f32 v[16:17], v[116:117], v[16:17]
	v_max_f32_e32 v18, v88, v88
	v_pk_add_f32 v[16:17], v[58:59], v[16:17]
	v_lshlrev_b32_e32 v44, 3, v64
	v_pk_add_f32 v[16:17], v[118:119], v[16:17]
	v_sub_u32_e32 v44, v65, v44
	v_pk_add_f32 v[16:17], v[62:63], v[16:17]
	v_add_u32_e32 v44, v44, v214
	v_pk_add_f32 v[16:17], v[16:17], v[16:17] op_sel_hi:[0,1]
	v_max_f32_e32 v16, v89, v89
	v_max_f32_e32 v16, v18, v16
	v_max3_f32 v18, v90, v91, v73
	v_max3_f32 v16, v16, v72, v74
	v_max3_f32 v16, v16, v75, v92
	v_max3_f32 v18, v18, v94, v95
	v_max3_f32 v16, v16, v93, v76
	v_max3_f32 v18, v18, v78, v79
	v_max3_f32 v16, v16, v77, v96
	v_max3_f32 v18, v18, v98, v99
	v_max3_f32 v16, v16, v97, v80
	v_max3_f32 v18, v18, v82, v83
	v_max3_f32 v16, v16, v81, v100
	v_max3_f32 v18, v18, v102, v103
	v_max3_f32 v16, v16, v101, v84
	v_max3_f32 v18, v18, v86, v87
	v_max3_f32 v16, v16, v85, v18
	v_mov_b32_e32 v18, v16
	s_nop 1
	v_permlane32_swap_b32_e32 v16, v18
	v_max_f32_e32 v18, v18, v18
	v_max_f32_e32 v16, v16, v16
	v_max_f32_e32 v104, v16, v18
	v_add_u32_e32 v140, 0x2000, v44
	v_add_u32_e32 v141, 0x3000, v44
	v_sub_f32_e32 v40, v88, v104
	v_sub_f32_e32 v41, v89, v104
	v_sub_f32_e32 v42, v90, v104
	v_sub_f32_e32 v43, v91, v104
	ds_read2_b64 v[88:91], v140 offset0:128 offset1:130
	ds_read2_b64 v[122:125], v141 offset0:160 offset1:162
	v_exp_f32_e64 v2, -v48
	v_exp_f32_e64 v18, -v104
	v_sub_f32_e32 v45, v92, v104
	v_sub_f32_e32 v46, v93, v104
	v_cvt_pk_bf16_f32 v32, v32, v33
	v_cvt_pk_bf16_f32 v33, v34, v35
	v_cvt_pk_bf16_f32 v34, v36, v37
	v_sub_f32_e32 v36, v94, v104
	v_sub_f32_e32 v37, v95, v104
	v_exp_f32_e32 v126, v40
	v_exp_f32_e32 v127, v41
	v_exp_f32_e32 v128, v42
	v_exp_f32_e32 v129, v43
	v_exp_f32_e32 v130, v45
	v_exp_f32_e32 v131, v46
	v_exp_f32_e32 v132, v36
	v_exp_f32_e32 v133, v37
	v_mul_f32_e32 v0, 0, v2
	v_mov_b32_e32 v49, v0
	v_mov_b32_e32 v16, v161
	v_pk_add_f32 v[216:217], v[48:49], v[16:17]
	v_mul_f32_e32 v16, 0, v18
	v_mov_b32_e32 v1, v0
	v_mov_b32_e32 v2, v0
	v_mov_b32_e32 v3, v0
	v_mov_b32_e32 v4, v0
	v_mov_b32_e32 v5, v0
	v_mov_b32_e32 v6, v0
	v_mov_b32_e32 v7, v0
	v_mov_b32_e32 v8, v0
	v_mov_b32_e32 v9, v0
	v_mov_b32_e32 v10, v0
	v_mov_b32_e32 v11, v0
	v_mov_b32_e32 v12, v0
	v_mov_b32_e32 v13, v0
	v_mov_b32_e32 v14, v0
	v_mov_b32_e32 v15, v0
	v_pk_add_f32 v[48:49], v[216:217], 0 neg_lo:[1,1] neg_hi:[1,1]
	v_mov_b32_e32 v17, v16
	v_mov_b32_e32 v18, v16
	v_mov_b32_e32 v19, v16
	v_mov_b32_e32 v20, v16
	v_mov_b32_e32 v21, v16
	v_mov_b32_e32 v22, v16
	v_mov_b32_e32 v23, v16
	v_mov_b32_e32 v24, v16
	v_mov_b32_e32 v25, v16
	v_mov_b32_e32 v26, v16
	v_mov_b32_e32 v27, v16
	v_mov_b32_e32 v28, v16
	v_mov_b32_e32 v29, v16
	v_mov_b32_e32 v30, v16
	v_mov_b32_e32 v31, v16
	v_cvt_pk_bf16_f32 v35, v38, v39
	v_cvt_pk_bf16_f32 v92, v126, v127
	v_cvt_pk_bf16_f32 v93, v128, v129
	v_cvt_pk_bf16_f32 v94, v130, v131
	v_cvt_pk_bf16_f32 v95, v132, v133
	v_sub_f32_e32 v49, v72, v104
	v_sub_f32_e32 v121, v73, v104
	v_sub_f32_e32 v134, v74, v104
	v_sub_f32_e32 v135, v75, v104
	v_sub_f32_e32 v136, v76, v104
	v_sub_f32_e32 v137, v77, v104
	v_sub_f32_e32 v138, v78, v104
	v_sub_f32_e32 v139, v79, v104
	s_waitcnt lgkmcnt(1)
	v_mfma_f32_32x32x16_bf16 v[64:79], v[88:91], v[32:35], v[0:15]
	v_sub_f32_e32 v142, v80, v104
	v_sub_f32_e32 v80, v96, v104
	v_sub_f32_e32 v143, v97, v104
	v_sub_f32_e32 v144, v98, v104
	v_sub_f32_e32 v145, v99, v104
	ds_read2_b64 v[96:99], v141 offset0:164 offset1:166
	v_mov_b32_e32 v105, v16
	s_waitcnt lgkmcnt(1)
	v_mfma_f32_32x32x16_bf16 v[0:15], v[122:125], v[32:35], v[0:15]
	v_cvt_pk_bf16_f32 v54, v54, v55
	v_cvt_pk_bf16_f32 v55, v56, v57
	v_cvt_pk_bf16_f32 v56, v58, v59
	v_cvt_pk_bf16_f32 v57, v62, v63
	v_mov_b32_e32 v50, v48
	v_mov_b32_e32 v51, v48
	v_mov_b32_e32 v52, v48
	v_mfma_f32_32x32x16_bf16 v[32:47], v[88:91], v[92:95], v[16:31]
	ds_read2_b64 v[88:91], v140 offset0:132 offset1:134
	v_mov_b32_e32 v53, v48
	v_mfma_f32_32x32x16_bf16 v[16:31], v[122:125], v[92:95], v[16:31]
	v_sub_f32_e32 v122, v100, v104
	v_sub_f32_e32 v123, v101, v104
	v_cvt_pk_bf16_f32 v93, v114, v115
	v_sub_f32_e32 v114, v102, v104
	v_sub_f32_e32 v115, v103, v104
	v_cvt_pk_bf16_f32 v92, v112, v113
	v_exp_f32_e32 v100, v80
	v_exp_f32_e32 v101, v143
	v_exp_f32_e32 v102, v144
	v_exp_f32_e32 v103, v145
	v_exp_f32_e32 v112, v122
	v_exp_f32_e32 v113, v123
	v_exp_f32_e32 v114, v114
	v_exp_f32_e32 v115, v115
	v_cvt_pk_bf16_f32 v94, v116, v117
	v_cvt_pk_bf16_f32 v95, v118, v119
	v_sub_f32_e32 v116, v81, v104
	v_sub_f32_e32 v117, v82, v104
	s_waitcnt lgkmcnt(0)
	v_mfma_f32_32x32x16_bf16 v[64:79], v[88:91], v[92:95], v[64:79]
	v_sub_f32_e32 v118, v83, v104
	ds_read2_b64 v[80:83], v140 offset0:136 offset1:138
	v_sub_f32_e32 v119, v84, v104
	v_sub_f32_e32 v122, v85, v104
	v_exp_f32_e32 v84, v49
	v_exp_f32_e32 v85, v121
	v_sub_f32_e32 v123, v86, v104
	v_mfma_f32_32x32x16_bf16 v[0:15], v[96:99], v[92:95], v[0:15]
	v_cvt_pk_bf16_f32 v92, v100, v101
	v_cvt_pk_bf16_f32 v93, v102, v103
	v_cvt_pk_bf16_f32 v94, v112, v113
	v_cvt_pk_bf16_f32 v95, v114, v115
	v_sub_f32_e32 v49, v87, v104
	s_nop 0
	v_mfma_f32_32x32x16_bf16 v[32:47], v[88:91], v[92:95], v[32:47]
	v_cvt_pk_bf16_f32 v88, v60, v61
	v_add_f32_e64 v60, v126, 0
	v_add_f32_e64 v61, v127, 0
	v_cvt_pk_bf16_f32 v89, v106, v107
	v_cvt_pk_bf16_f32 v90, v108, v109
	v_cvt_pk_bf16_f32 v91, v110, v111
	v_pk_add_f32 v[60:61], v[84:85], v[60:61]
	v_cvt_pk_bf16_f32 v84, v84, v85
	v_mfma_f32_32x32x16_bf16 v[16:31], v[96:99], v[92:95], v[16:31]
	ds_read2_b64 v[92:95], v141 offset0:168 offset1:170
	v_exp_f32_e32 v96, v134
	v_exp_f32_e32 v97, v135
	v_exp_f32_e32 v98, v136
	v_exp_f32_e32 v99, v137
	v_pk_add_f32 v[60:61], v[128:129], v[60:61]
	v_cvt_pk_bf16_f32 v85, v96, v97
	s_waitcnt lgkmcnt(1)
	v_mfma_f32_32x32x16_bf16 v[64:79], v[80:83], v[88:91], v[64:79]
	v_add_f32_e64 v60, v96, v60
	v_add_f32_e64 v61, v97, v61
	v_cvt_pk_bf16_f32 v86, v98, v99
	v_add_f32_e64 v60, v130, v60
	v_add_f32_e64 v61, v131, v61
	v_pk_add_f32 v[60:61], v[98:99], v[60:61]
	s_nop 0
	v_pk_add_f32 v[60:61], v[132:133], v[60:61]
	s_waitcnt lgkmcnt(0)
	v_mfma_f32_32x32x16_bf16 v[0:15], v[92:95], v[88:91], v[0:15]
	v_exp_f32_e32 v88, v138
	v_exp_f32_e32 v89, v139
	v_exp_f32_e32 v90, v142
	v_exp_f32_e32 v91, v116
	v_cvt_pk_bf16_f32 v87, v88, v89
	v_pk_add_f32 v[88:89], v[88:89], v[60:61]
	s_nop 0
	v_mfma_f32_32x32x16_bf16 v[32:47], v[80:83], v[84:87], v[32:47]
	ds_read2_b64 v[80:83], v140 offset0:140 offset1:142
	ds_read2_b64 v[58:61], v141 offset0:172 offset1:174
	v_add_f32_e64 v62, v100, v88
	v_add_f32_e64 v63, v101, v89
	v_exp_f32_e32 v88, v123
	v_exp_f32_e32 v89, v49
	v_pk_add_f32 v[62:63], v[90:91], v[62:63]
	v_add3_u32 v49, 16, v203, v208
	v_mfma_f32_32x32x16_bf16 v[16:31], v[92:95], v[84:87], v[16:31]
	v_exp_f32_e32 v84, v117
	v_exp_f32_e32 v85, v118
	v_exp_f32_e32 v86, v119
	v_exp_f32_e32 v87, v122
	v_pk_add_f32 v[62:63], v[102:103], v[62:63]
	s_nop 0
	v_pk_add_f32 v[62:63], v[84:85], v[62:63]
	s_waitcnt lgkmcnt(1)
	v_mfma_f32_32x32x16_bf16 v[64:79], v[80:83], v[54:57], v[64:79]
	v_add_f32_e64 v62, v112, v62
	v_add_f32_e64 v63, v113, v63
	v_add_f32_e64 v62, v86, v62
	v_add_f32_e64 v63, v87, v63
	v_add_f32_e64 v62, v114, v62
	v_add_f32_e64 v63, v115, v63
	v_pk_add_f32 v[62:63], v[88:89], v[62:63]
	s_waitcnt lgkmcnt(0)
	v_mfma_f32_32x32x16_bf16 v[0:15], v[58:61], v[54:57], v[0:15]
	v_cvt_pk_bf16_f32 v54, v90, v91
	v_cvt_pk_bf16_f32 v55, v84, v85
	v_cvt_pk_bf16_f32 v56, v86, v87
	v_cvt_pk_bf16_f32 v57, v88, v89
	v_pk_add_f32 v[62:63], v[62:63], v[62:63] op_sel_hi:[0,1]
	v_mov_b32_e32 v62, v161
	v_pk_add_f32 v[222:223], v[104:105], v[62:63]
	v_mfma_f32_32x32x16_bf16 v[32:47], v[80:83], v[54:57], v[32:47]
	v_add_f32_e64 v80, -v222, neg(0)
	v_add_f32_e64 v81, -v223, neg(0)
	v_mov_b32_e32 v62, v48
	v_mov_b32_e32 v81, v80
	v_mov_b32_e32 v82, v80
	v_mov_b32_e32 v83, v80
	v_mov_b32_e32 v84, v80
	v_mov_b32_e32 v85, v80
	v_mfma_f32_32x32x16_bf16 v[16:31], v[58:61], v[54:57], v[16:31]
	v_add_u32_e32 v54, 0x6a00, v49
	v_add_u32_e32 v49, v49, v120
	s_waitcnt vmcnt(1)
	ds_write_b128 v49, v[194:197] offset:17920
	s_waitcnt vmcnt(0)
	ds_write2_b64 v54, v[198:199], v[200:201] offset1:1
	v_mov_b32_e32 v86, v80
	v_mov_b32_e32 v87, v80
	v_mov_b32_e32 v88, v80
	v_mov_b32_e32 v89, v80
	v_mov_b32_e32 v90, v80
	v_mov_b32_e32 v91, v80
	v_mov_b32_e32 v92, v80
	v_mov_b32_e32 v93, v80
	v_mov_b32_e32 v94, v80
	v_mov_b32_e32 v95, v80
	v_mov_b32_e32 v49, v48
	v_mov_b32_e32 v54, v48
	v_mov_b32_e32 v55, v48
	v_mov_b32_e32 v56, v48
	v_mov_b32_e32 v57, v48
	v_mov_b32_e32 v58, v48
	v_mov_b32_e32 v59, v48
	v_mov_b32_e32 v60, v48
	v_mov_b32_e32 v61, v48
	v_mov_b32_e32 v63, v48
	s_waitcnt lgkmcnt(0)
	s_barrier
	s_cmp_lt_u32 s11, 3
	s_cselect_b64 s[2:3], -1, 0
	s_cmp_gt_u32 s11, 2
	s_cbranch_scc1 .LBB0_350
